# next-unit L2 prefetch added to gdn prep (on top of part 1 rewrite)
# baseline (speedup 1.0000x reference)
; #define LAS __attribute__((address_space(3)))
; __device__ __forceinline__ unsigned f2bf(float f) { return pk2(f, f) & 0xffffu; }
; __device__ __forceinline__ void gdn_prep_unit(const Args& c, int ug, int l, LAS unsigned char* lds) {
;     ...
;                 const float dcy = (i >= j) ? __expf(gcs[i] - gj) : 0.f;
;                 Mm[i * 68 + j] = (i > j) ? bet[i] * ckk[e] * dcy : 0.f;
;                 ((bf16*)(wsl + WS_AT))[(size_t)ug * 4096 + i * 64 + j] = (bf16)f2bf(cqk[e] * dcy);
;             }
;         }
;     }
;     __syncthreads();
;     if (tid < 256) {
;         const int col = tid & 127; const bool isw = tid >= 128;
;         int vz = 0; asm volatile("" : "+v"(vz));
;         const LAS float* Mz = Mm + vz; const LAS float* betz = bet + vz; const LAS float* egz = egs + vz;
;         float x[64];
; #pragma unroll
;         for (int i = 0; i < 64; ++i) x[i] = isw ? kf[i * 132 + col] * betz[i] * egz[i] : vf[i * 132 + col] * betz[i];
.LBB0_662:
	s_or_b64 exec, exec, s[2:3]
	v_add3_u32 v2, s0, v33, v6
	ds_write_b32 v2, v0
	v_mul_f32_e32 v0, v5, v3
	s_movk_i32 s1, 0x100
	v_cvt_pk_bf16_f32 v0, v0, s0
	v_cmp_gt_i32_e32 vcc, s1, v149
	flat_store_short v[16:17], v0 offset:32
	s_waitcnt lgkmcnt(0)
	s_barrier
	s_add_i32 s0, s17, s58
	s_and_b32 s1, s0, 3
	s_lshr_b32 s2, s0, 7
	s_lshl_b32 s2, s2, 11
	s_lshr_b32 s3, s0, 2
	s_and_b32 s3, s3, 31
	s_lshl_b32 s3, s3, 6
	s_or_b32 s2, s2, s3
	s_lshl_b32 s1, s1, 8
	s_addk_i32 s1, 0xe80
	v_lshrrev_b32_e32 v244, 3, v149
	v_and_b32_e32 v245, 7, v149
	v_add_u32_e32 v244, s2, v244
	v_mul_u32_u24_e32 v244, 0x3800, v244
	v_and_b32_e32 v246, 6, v245
	v_lshlrev_b32_e32 v246, 9, v246
	v_and_b32_e32 v245, 1, v245
	v_lshl_add_u32 v246, v245, 7, v246
	v_add_u32_e32 v244, v244, v246
	v_add_u32_e32 v244, s1, v244
	s_add_u32 s2, s42, 0xa800000
	s_addc_u32 s3, s43, 0
	global_load_dword v244, v244, s[2:3]
	s_and_saveexec_b64 s[6:7], vcc
	s_cbranch_execz .LBB0_623
	v_readfirstlane_b32 s0, v149
	v_and_b32_e32 v68, 0x7f, v149
	v_lshlrev_b32_e32 v68, 2, v68
	v_mov_b32_e32 v2, 0x10800
	v_mov_b32_e32 v3, 0x14d00
	s_nop 3
	s_cmp_ge_u32 s0, 0x80
	s_cselect_b32 s1, 0, 0x8400
	s_cselect_b32 s2, 1, 0
	v_add_u32_e32 v68, s1, v68
	ds_read_b128 v[204:207], v3 offset:0
	ds_read_b128 v[208:211], v3 offset:16
	ds_read_b128 v[212:215], v3 offset:256
	ds_read_b128 v[216:219], v3 offset:272
	ds_read_b32 v4, v68
	ds_read_b32 v5, v68 offset:528
	ds_read_b32 v6, v68 offset:1056
	ds_read_b32 v7, v68 offset:1584
	ds_read_b32 v8, v68 offset:2112
	ds_read_b32 v9, v68 offset:2640
	ds_read_b32 v10, v68 offset:3168
	ds_read_b32 v11, v68 offset:3696
	s_waitcnt lgkmcnt(0)
	v_mul_f32_e32 v4, v204, v4
	v_mul_f32_e32 v5, v205, v5
	v_mul_f32_e32 v6, v206, v6
	v_mul_f32_e32 v7, v207, v7
	v_mul_f32_e32 v8, v208, v8
	v_mul_f32_e32 v9, v209, v9
	v_mul_f32_e32 v10, v210, v10
	v_mul_f32_e32 v11, v211, v11
	s_cmp_eq_u32 s2, 0
	s_cbranch_scc1 .Lgdn4_noeg_0
	v_mul_f32_e32 v4, v4, v212
	v_mul_f32_e32 v5, v5, v213
	v_mul_f32_e32 v6, v6, v214
	v_mul_f32_e32 v7, v7, v215
	v_mul_f32_e32 v8, v8, v216
	v_mul_f32_e32 v9, v9, v217
	v_mul_f32_e32 v10, v10, v218
	v_mul_f32_e32 v11, v11, v219
